# norm loops consolidated + post_phase loops: all 8 item loads up front, next-iteration L2 touch
# baseline (speedup 1.0000x reference)
; __device__ __forceinline__ unsigned pk2(float lo, float hi) { return f2bf(lo) | (f2bf(hi) << 16); }
; __device__ __forceinline__ void unpack8(const v4u& w, float (&f)[8]) { f[0] = bflo(w.x); f[1] = bfhi(w.x); f[2] = bflo(w.y); f[3] = bfhi(w.y); f[4] = bflo(w.z); f[5] = bfhi(w.z); f[6] = bflo(w.w); f[7] = bfhi(w.w); }
; __device__ __forceinline__ void post_phase(bf16* O, const bf16* Gt, int nheads, int lane, int wave, int vcu, int G) {
;     ...
;     for (int it_ = 0; it_ < nit; ++it_) {
;         const int it0 = xdeal ? (gw >> 8) * SEQ * nheads + 4 * (gw & 255) + 1024 * it_ : 4 * gw + it_ * 4 * NGW;
;         if (it0 >= nitems) break;
;         v4u ov[4], gv[4];
; #pragma unroll
;         for (int u = 0; u < 4; ++u) { const size_t off = (size_t)(it0 + u) * 512 + 8 * lane; ov[u] = *(const v4u*)(O + off); gv[u] = *(const v4u*)(Gt + off); }
; #pragma unroll
;         for (int u = 0; u < 4; ++u) { const size_t off = (size_t)(it0 + u) * 512 + 8 * lane;
;             float o[8], g[8]; unpack8(ov[u], o); unpack8(gv[u], g);
;             float ss = 0.f;
; #pragma unroll
;             for (int e = 0; e < 8; ++e) ss += o[e] * o[e];
;             const float rstd = rsqrtf(wave_sum(ss) * (1.0f / 512.0f) + EPS);
;             v4u w; w.x = pk2(g[0] * o[0] * rstd, g[1] * o[1] * rstd); w.y = pk2(g[2] * o[2] * rstd, g[3] * o[3] * rstd); w.z = pk2(g[4] * o[4] * rstd, g[5] * o[5] * rstd); w.w = pk2(g[6] * o[6] * rstd, g[7] * o[7] * rstd);
;             *(v4u*)(O + off) = w; }
.LBB0_501:
	s_mov_b64 s[100:101], 0x100000
	s_ashr_i32 s15, s14, 31
	s_lshl_b64 s[20:21], s[14:15], 10
	v_or_b32_e32 v2, s20, v1
	v_mov_b32_e32 v3, s21
	s_add_u32 s14, s20, 0x400
	v_lshl_add_u64 v[6:7], s[6:7], 0, v[2:3]
	s_addc_u32 s15, s21, 0
	v_lshl_add_u64 v[8:9], s[8:9], 0, v[2:3]
	global_load_dwordx4 v[2:5], v[6:7], off
	global_load_dwordx4 v[22:25], v[8:9], off
	global_load_dwordx4 v[128:131], v[6:7], off offset:2048
	global_load_dwordx4 v[132:135], v[8:9], off offset:2048
	global_load_dwordx4 v[136:139], v[6:7], off offset:3072
	global_load_dwordx4 v[140:143], v[8:9], off offset:3072
	v_or_b32_e32 v6, s14, v1
	v_mov_b32_e32 v7, s15
	v_lshl_add_u64 v[8:9], s[6:7], 0, v[6:7]
	v_lshl_add_u64 v[12:13], s[8:9], 0, v[6:7]
	v_lshl_add_u64 v[144:145], v[8:9], 0, s[100:101]
	v_lshl_add_u64 v[146:147], v[12:13], 0, s[100:101]
	global_load_dwordx4 v[6:9], v[8:9], off
	s_nop 0
	global_load_dwordx4 v[26:29], v[12:13], off
	global_load_dwordx4 v[148:151], v[144:145], off offset:-1024
	global_load_dwordx4 v[148:151], v[144:145], off
	global_load_dwordx4 v[148:151], v[144:145], off offset:1024
	global_load_dwordx4 v[148:151], v[144:145], off offset:2048
	global_load_dwordx4 v[148:151], v[146:147], off offset:-1024
	global_load_dwordx4 v[148:151], v[146:147], off
	global_load_dwordx4 v[148:151], v[146:147], off offset:1024
	global_load_dwordx4 v[148:151], v[146:147], off offset:2048
	v_cmp_lt_i32_e32 vcc, v16, v15
	s_add_u32 s18, s20, 0x800
	s_addc_u32 s19, s21, 0
	v_cndmask_b32_e32 v12, v14, v16, vcc
	v_cmp_lt_i32_e32 vcc, v17, v15
	v_lshlrev_b32_e32 v64, 2, v12
	s_add_u32 s16, s20, 0xc00
	v_cndmask_b32_e32 v13, v14, v17, vcc
	v_cmp_lt_i32_e32 vcc, v18, v15
	v_lshlrev_b32_e32 v65, 2, v13
	s_addc_u32 s17, s21, 0
	v_cndmask_b32_e32 v30, v14, v18, vcc
	v_cmp_lt_i32_e32 vcc, v19, v15
	v_lshlrev_b32_e32 v66, 2, v30
	s_add_i32 s23, s23, 1
	v_cndmask_b32_e32 v31, v14, v19, vcc
	v_cmp_lt_i32_e32 vcc, v20, v15
	v_lshlrev_b32_e32 v67, 2, v31
	s_addk_i32 s22, 0x400
	v_cndmask_b32_e32 v32, v14, v20, vcc
	v_cmp_lt_i32_e32 vcc, v21, v15
	v_lshlrev_b32_e32 v68, 2, v32
	s_add_i32 s3, s3, -1
	v_cndmask_b32_e32 v33, v14, v21, vcc
	v_lshlrev_b32_e32 v69, 2, v33
	s_cmp_eq_u32 s3, 0
	s_waitcnt vmcnt(8)
	v_lshlrev_b32_e32 v32, 16, v2
	v_and_b32_e32 v2, 0xffff0000, v2
	v_lshlrev_b32_e32 v13, 16, v3
	v_lshlrev_b32_e32 v12, 16, v22
	v_lshlrev_b32_e32 v33, 16, v23
	v_lshlrev_b32_e32 v37, 16, v7
	v_and_b32_e32 v49, 0xffff0000, v7
	v_and_b32_e32 v48, 0xffff0000, v26
	v_lshlrev_b32_e32 v50, 16, v6
	v_and_b32_e32 v7, 0xffff0000, v27
	v_and_b32_e32 v6, 0xffff0000, v6
	v_lshlrev_b32_e32 v36, 16, v26
	v_lshlrev_b32_e32 v51, 16, v27
	v_pk_mul_f32 v[60:61], v[48:49], v[6:7]
	v_mov_b32_e32 v7, v2
	v_lshlrev_b32_e32 v40, 16, v4
	v_and_b32_e32 v42, 0xffff0000, v4
	v_lshlrev_b32_e32 v54, 16, v8
	v_and_b32_e32 v56, 0xffff0000, v8
	v_pk_mul_f32 v[58:59], v[36:37], v[50:51]
	v_mov_b32_e32 v51, v32
	v_pk_mul_f32 v[6:7], v[6:7], v[6:7]
	v_and_b32_e32 v31, 0xffff0000, v3
	v_and_b32_e32 v30, 0xffff0000, v22
	v_and_b32_e32 v3, 0xffff0000, v23
	v_lshlrev_b32_e32 v23, 16, v5
	v_and_b32_e32 v39, 0xffff0000, v5
	v_pk_mul_f32 v[44:45], v[12:13], v[32:33]
	v_mov_b32_e32 v4, v42
	v_mov_b32_e32 v5, v40
	v_lshlrev_b32_e32 v27, 16, v9
	v_and_b32_e32 v53, 0xffff0000, v9
	v_mov_b32_e32 v8, v56
	v_mov_b32_e32 v9, v54
	v_mov_b32_e32 v12, v37
	v_pk_fma_f32 v[6:7], v[50:51], v[50:51], v[6:7]
	v_pk_mul_f32 v[46:47], v[30:31], v[2:3]
	v_pk_mul_f32 v[4:5], v[4:5], v[4:5]
	v_mov_b32_e32 v30, v49
	v_pk_mul_f32 v[8:9], v[8:9], v[8:9]
	v_pk_fma_f32 v[6:7], v[12:13], v[12:13], v[6:7]
	v_mov_b32_e32 v34, v39
	v_mov_b32_e32 v35, v23
	v_mov_b32_e32 v62, v53
	v_mov_b32_e32 v63, v27
	v_mov_b32_e32 v3, v5
	v_mov_b32_e32 v2, v9
	v_pk_fma_f32 v[6:7], v[30:31], v[30:31], v[6:7]
	v_pk_mul_f32 v[34:35], v[34:35], v[34:35]
	v_pk_mul_f32 v[32:33], v[62:63], v[62:63]
	v_mov_b32_e32 v9, v4
	v_pk_add_f32 v[2:3], v[2:3], v[6:7]
	v_mov_b32_e32 v5, v35
	v_mov_b32_e32 v4, v33
	v_pk_add_f32 v[2:3], v[8:9], v[2:3]
	v_mov_b32_e32 v33, v34
	v_pk_add_f32 v[2:3], v[4:5], v[2:3]
	v_or_b32_e32 v6, s18, v1
	v_pk_add_f32 v[2:3], v[32:33], v[2:3]
	ds_bpermute_b32 v5, v64, v3
	ds_bpermute_b32 v4, v64, v2
	v_mov_b32_e32 v7, s19
	v_or_b32_e32 v12, s16, v1
	v_mov_b32_e32 v13, s17
	v_lshl_add_u64 v[8:9], s[6:7], 0, v[6:7]
	s_waitcnt lgkmcnt(0)
	v_pk_add_f32 v[2:3], v[2:3], v[4:5]
	ds_bpermute_b32 v5, v65, v3
	ds_bpermute_b32 v4, v65, v2
	v_lshl_add_u64 v[6:7], s[8:9], 0, v[6:7]
	v_mov_b64_e32 v[30:31], v[128:129]
	v_mov_b64_e32 v[32:33], v[130:131]
	s_nop 0
	v_mov_b64_e32 v[6:7], v[132:133]
	v_mov_b64_e32 v[8:9], v[134:135]
	v_lshlrev_b32_e32 v22, 16, v24
	v_and_b32_e32 v38, 0xffff0000, v24
	s_waitcnt lgkmcnt(0)
	v_pk_add_f32 v[2:3], v[2:3], v[4:5]
	ds_bpermute_b32 v5, v66, v3
	ds_bpermute_b32 v4, v66, v2
	v_lshlrev_b32_e32 v41, 16, v25
	v_and_b32_e32 v43, 0xffff0000, v25
	v_pk_mul_f32 v[38:39], v[38:39], v[42:43]
	v_pk_mul_f32 v[22:23], v[22:23], v[40:41]
	s_waitcnt lgkmcnt(0)
	v_pk_add_f32 v[48:49], v[2:3], v[4:5]
	v_lshl_add_u64 v[2:3], s[6:7], 0, v[12:13]
	v_lshl_add_u64 v[4:5], s[8:9], 0, v[12:13]
	v_mov_b64_e32 v[34:35], v[136:137]
	v_mov_b64_e32 v[36:37], v[138:139]
	s_nop 0
	v_mov_b64_e32 v[2:3], v[140:141]
	v_mov_b64_e32 v[4:5], v[142:143]
	ds_bpermute_b32 v51, v67, v49
	ds_bpermute_b32 v50, v67, v48
	v_lshlrev_b32_e32 v26, 16, v28
	v_and_b32_e32 v52, 0xffff0000, v28
	v_lshlrev_b32_e32 v55, 16, v29
	v_and_b32_e32 v57, 0xffff0000, v29
	s_waitcnt lgkmcnt(0)
	v_pk_add_f32 v[12:13], v[48:49], v[50:51]
	ds_bpermute_b32 v49, v68, v13
	ds_bpermute_b32 v48, v68, v12
	v_lshl_add_u64 v[40:41], v[10:11], 0, s[20:21]
	v_pk_mul_f32 v[26:27], v[26:27], v[54:55]
	s_waitcnt lgkmcnt(0)
; __device__ __forceinline__ unsigned pk2(float lo, float hi) { return f2bf(lo) | (f2bf(hi) << 16); }
; __device__ __forceinline__ void unpack8(const v4u& w, float (&f)[8]) { f[0] = bflo(w.x); f[1] = bfhi(w.x); f[2] = bflo(w.y); f[3] = bfhi(w.y); f[4] = bflo(w.z); f[5] = bfhi(w.z); f[6] = bflo(w.w); f[7] = bfhi(w.w); }
; __device__ __forceinline__ void post_phase(bf16* O, const bf16* Gt, int nheads, int lane, int wave, int vcu, int G) {
;     const int gw = vcu * NWAVES + wave, NGW = G * NWAVES, nitems = M * nheads;
;     const bool xdeal = (G == 256);
;     const int nit = xdeal ? 2 * nheads : (nitems + 4 * NGW - 1) / (4 * NGW);
;     for (int it_ = 0; it_ < nit; ++it_) {
;         const int it0 = xdeal ? (gw >> 8) * SEQ * nheads + 4 * (gw & 255) + 1024 * it_ : 4 * gw + it_ * 4 * NGW;
;         if (it0 >= nitems) break;
;         v4u ov[4], gv[4];
; #pragma unroll
;         for (int u = 0; u < 4; ++u) { const size_t off = (size_t)(it0 + u) * 512 + 8 * lane; ov[u] = *(const v4u*)(O + off); gv[u] = *(const v4u*)(Gt + off); }
; #pragma unroll
;         for (int u = 0; u < 4; ++u) { const size_t off = (size_t)(it0 + u) * 512 + 8 * lane;
;             float o[8], g[8]; unpack8(ov[u], o); unpack8(gv[u], g);
;             float ss = 0.f;
; #pragma unroll
;             for (int e = 0; e < 8; ++e) ss += o[e] * o[e];
;             const float rstd = rsqrtf(wave_sum(ss) * (1.0f / 512.0f) + EPS);
;             v4u w; w.x = pk2(g[0] * o[0] * rstd, g[1] * o[1] * rstd); w.y = pk2(g[2] * o[2] * rstd, g[3] * o[3] * rstd); w.z = pk2(g[4] * o[4] * rstd, g[5] * o[5] * rstd); w.w = pk2(g[6] * o[6] * rstd, g[7] * o[7] * rstd);
;             *(v4u*)(O + off) = w; }
;     }
; }
	v_pk_add_f32 v[12:13], v[12:13], v[48:49]
	ds_bpermute_b32 v25, v69, v13
	ds_bpermute_b32 v24, v69, v12
	s_waitcnt lgkmcnt(0)
	v_pk_add_f32 v[24:25], v[12:13], v[24:25]
	v_mov_b64_e32 v[12:13], s[12:13]
	v_pk_fma_f32 v[42:43], v[24:25], s[10:11], v[12:13] op_sel_hi:[1,0,0]
	v_lshlrev_b32_e32 v51, 16, v35
	v_mul_f32_e32 v24, 0x4b800000, v43
	v_cmp_gt_f32_e32 vcc, s25, v43
	v_lshlrev_b32_e32 v50, 16, v2
	v_lshlrev_b32_e32 v55, 16, v3
	v_cndmask_b32_e32 v24, v43, v24, vcc
	v_rsq_f32_e32 v24, v24
	v_and_b32_e32 v3, 0xffff0000, v3
	v_lshlrev_b32_e32 v54, 16, v34
	v_mul_f32_e32 v25, 0x45800000, v24
	v_cndmask_b32_e32 v24, v24, v25, vcc
	v_pk_mul_f32 v[28:29], v[44:45], v[24:25] op_sel_hi:[1,0]
	v_pk_mul_f32 v[44:45], v[46:47], v[24:25] op_sel_hi:[1,0]
	v_pk_mul_f32 v[22:23], v[22:23], v[24:25] op_sel_hi:[1,0]
	v_bfe_u32 v43, v45, 16, 1
	v_pk_mul_f32 v[24:25], v[38:39], v[24:25] op_sel_hi:[1,0]
	v_add3_u32 v43, v45, v43, s26
	v_bfe_u32 v45, v22, 16, 1
	v_bfe_u32 v39, v24, 16, 1
	v_add3_u32 v22, v22, v45, s26
	v_add3_u32 v24, v24, v39, s26
	v_lshrrev_b32_e32 v22, 16, v22
	v_bfe_u32 v38, v25, 16, 1
	v_and_or_b32 v24, v24, s24, v22
	v_mul_f32_e32 v22, 0x4b800000, v42
	v_cmp_gt_f32_e32 vcc, s25, v42
	v_bfe_u32 v46, v44, 16, 1
	v_add3_u32 v25, v25, v38, s26
	v_bfe_u32 v38, v28, 16, 1
	v_cndmask_b32_e32 v22, v42, v22, vcc
	v_add3_u32 v44, v44, v46, s26
	v_bfe_u32 v39, v29, 16, 1
	v_bfe_u32 v46, v23, 16, 1
	v_add3_u32 v28, v28, v38, s26
	v_rsq_f32_e32 v38, v22
	v_add3_u32 v23, v23, v46, s26
	v_add3_u32 v29, v29, v39, s26
	v_lshrrev_b32_e32 v28, 16, v28
	v_lshrrev_b32_e32 v29, 16, v29
	v_lshrrev_b32_e32 v23, 16, v23
	v_and_or_b32 v25, v25, s24, v23
	v_and_or_b32 v23, v43, s24, v29
	v_and_or_b32 v22, v44, s24, v28
	global_store_dwordx4 v[40:41], v[22:25], off
	v_lshlrev_b32_e32 v42, 16, v32
	v_and_b32_e32 v44, 0xffff0000, v32
	v_mul_f32_e32 v22, 0x45800000, v38
	v_cndmask_b32_e32 v22, v38, v22, vcc
	v_pk_mul_f32 v[38:39], v[52:53], v[56:57]
	v_pk_mul_f32 v[24:25], v[58:59], v[22:23] op_sel_hi:[1,0]
	v_pk_mul_f32 v[28:29], v[60:61], v[22:23] op_sel_hi:[1,0]
	v_pk_mul_f32 v[26:27], v[26:27], v[22:23] op_sel_hi:[1,0]
	v_pk_mul_f32 v[22:23], v[38:39], v[22:23] op_sel_hi:[1,0]
	v_bfe_u32 v41, v28, 16, 1
	v_bfe_u32 v39, v22, 16, 1
	v_bfe_u32 v38, v23, 16, 1
	v_add3_u32 v43, v28, v41, s26
	v_add3_u32 v62, v22, v39, s26
	v_lshlrev_b32_e32 v22, 16, v6
	v_and_b32_e32 v28, 0xffff0000, v6
	v_and_b32_e32 v6, 0xffff0000, v30
	v_and_b32_e32 v53, 0xffff0000, v35
	v_and_b32_e32 v52, 0xffff0000, v2
	v_and_b32_e32 v2, 0xffff0000, v34
	v_add3_u32 v63, v23, v38, s26
	v_lshlrev_b32_e32 v38, 16, v30
	v_pk_mul_f32 v[56:57], v[52:53], v[2:3]
	v_mov_b32_e32 v3, v6
	v_bfe_u32 v40, v29, 16, 1
	v_lshlrev_b32_e32 v23, 16, v31
	v_lshlrev_b32_e32 v39, 16, v7
	v_pk_mul_f32 v[34:35], v[50:51], v[54:55]
	v_lshlrev_b32_e32 v50, 16, v36
	v_and_b32_e32 v52, 0xffff0000, v36
	v_mov_b32_e32 v55, v38
	v_pk_mul_f32 v[2:3], v[2:3], v[2:3]
	v_add3_u32 v45, v29, v40, s26
	v_and_b32_e32 v29, 0xffff0000, v31
	v_and_b32_e32 v7, 0xffff0000, v7
	v_pk_mul_f32 v[30:31], v[22:23], v[38:39]
	v_mov_b32_e32 v46, v44
	v_mov_b32_e32 v47, v42
	v_mov_b32_e32 v58, v52
	v_mov_b32_e32 v59, v50
	v_pk_fma_f32 v[2:3], v[54:55], v[54:55], v[2:3]
	v_mov_b32_e32 v22, v51
	v_pk_mul_f32 v[40:41], v[28:29], v[6:7]
	v_lshlrev_b32_e32 v7, 16, v33
	v_and_b32_e32 v33, 0xffff0000, v33
	v_pk_mul_f32 v[46:47], v[46:47], v[46:47]
	v_lshlrev_b32_e32 v39, 16, v37
	v_and_b32_e32 v37, 0xffff0000, v37
	v_pk_mul_f32 v[58:59], v[58:59], v[58:59]
	v_pk_fma_f32 v[2:3], v[22:23], v[22:23], v[2:3]
	v_mov_b32_e32 v28, v53
	v_mov_b32_e32 v48, v33
	v_mov_b32_e32 v49, v7
	v_mov_b32_e32 v60, v37
	v_mov_b32_e32 v61, v39
	v_pk_fma_f32 v[2:3], v[28:29], v[28:29], v[2:3]
	v_mov_b32_e32 v22, v59
	v_mov_b32_e32 v23, v47
	v_pk_mul_f32 v[48:49], v[48:49], v[48:49]
	v_pk_mul_f32 v[60:61], v[60:61], v[60:61]
	v_pk_add_f32 v[2:3], v[22:23], v[2:3]
	v_mov_b32_e32 v59, v46
	v_pk_add_f32 v[2:3], v[58:59], v[2:3]
	v_mov_b32_e32 v22, v61
	v_mov_b32_e32 v23, v49
	v_pk_add_f32 v[2:3], v[22:23], v[2:3]
	v_mov_b32_e32 v61, v48
	v_pk_add_f32 v[2:3], v[60:61], v[2:3]
	ds_bpermute_b32 v23, v64, v3
	ds_bpermute_b32 v22, v64, v2
	v_bfe_u32 v70, v24, 16, 1
	v_bfe_u32 v28, v27, 16, 1
	v_bfe_u32 v6, v26, 16, 1
	v_add3_u32 v27, v27, v28, s26
	s_waitcnt lgkmcnt(0)
; __device__ __forceinline__ unsigned pk2(float lo, float hi) { return f2bf(lo) | (f2bf(hi) << 16); }
; __device__ __forceinline__ void unpack8(const v4u& w, float (&f)[8]) { f[0] = bflo(w.x); f[1] = bfhi(w.x); f[2] = bflo(w.y); f[3] = bfhi(w.y); f[4] = bflo(w.z); f[5] = bfhi(w.z); f[6] = bflo(w.w); f[7] = bfhi(w.w); }
; __device__ __forceinline__ void post_phase(bf16* O, const bf16* Gt, int nheads, int lane, int wave, int vcu, int G) {
;     ...
;         for (int u = 0; u < 4; ++u) { const size_t off = (size_t)(it0 + u) * 512 + 8 * lane;
;             float o[8], g[8]; unpack8(ov[u], o); unpack8(gv[u], g);
;             float ss = 0.f;
; #pragma unroll
;             for (int e = 0; e < 8; ++e) ss += o[e] * o[e];
;             const float rstd = rsqrtf(wave_sum(ss) * (1.0f / 512.0f) + EPS);
;             v4u w; w.x = pk2(g[0] * o[0] * rstd, g[1] * o[1] * rstd); w.y = pk2(g[2] * o[2] * rstd, g[3] * o[3] * rstd); w.z = pk2(g[4] * o[4] * rstd, g[5] * o[5] * rstd); w.w = pk2(g[6] * o[6] * rstd, g[7] * o[7] * rstd);
;             *(v4u*)(O + off) = w; }
	v_pk_add_f32 v[2:3], v[2:3], v[22:23]
	ds_bpermute_b32 v23, v65, v3
	ds_bpermute_b32 v22, v65, v2
	v_add3_u32 v24, v24, v70, s26
	v_add3_u32 v6, v26, v6, s26
	v_lshrrev_b32_e32 v28, 16, v24
	v_lshrrev_b32_e32 v24, 16, v27
	s_waitcnt lgkmcnt(0)
	v_pk_add_f32 v[2:3], v[2:3], v[22:23]
	ds_bpermute_b32 v23, v66, v3
	ds_bpermute_b32 v22, v66, v2
	v_bfe_u32 v71, v25, 16, 1
	v_add3_u32 v25, v25, v71, s26
	v_lshrrev_b32_e32 v29, 16, v25
	v_lshrrev_b32_e32 v6, 16, v6
	s_waitcnt lgkmcnt(0)
	v_pk_add_f32 v[2:3], v[2:3], v[22:23]
	ds_bpermute_b32 v27, v67, v3
	ds_bpermute_b32 v26, v67, v2
	v_and_or_b32 v25, v63, s24, v24
	v_and_or_b32 v24, v62, s24, v6
	v_and_or_b32 v23, v45, s24, v29
	v_and_or_b32 v22, v43, s24, v28
	v_lshl_add_u64 v[28:29], v[10:11], 0, s[14:15]
	s_waitcnt lgkmcnt(0)
	v_pk_add_f32 v[2:3], v[2:3], v[26:27]
	global_store_dwordx4 v[28:29], v[22:25], off
	ds_bpermute_b32 v23, v68, v3
	ds_bpermute_b32 v22, v68, v2
	v_lshlrev_b32_e32 v6, 16, v8
	v_and_b32_e32 v32, 0xffff0000, v8
	v_lshlrev_b32_e32 v43, 16, v9
	v_and_b32_e32 v45, 0xffff0000, v9
	s_waitcnt lgkmcnt(0)
	v_pk_add_f32 v[2:3], v[2:3], v[22:23]
	ds_bpermute_b32 v9, v69, v3
	ds_bpermute_b32 v8, v69, v2
	v_lshlrev_b32_e32 v38, 16, v4
	v_and_b32_e32 v36, 0xffff0000, v4
	v_pk_mul_f32 v[6:7], v[6:7], v[42:43]
	v_pk_mul_f32 v[22:23], v[32:33], v[44:45]
	s_waitcnt lgkmcnt(0)
	v_pk_add_f32 v[2:3], v[2:3], v[8:9]
	v_lshlrev_b32_e32 v51, 16, v5
	v_pk_fma_f32 v[2:3], v[2:3], s[10:11], v[12:13] op_sel_hi:[1,0,0]
	v_and_b32_e32 v53, 0xffff0000, v5
	v_mul_f32_e32 v8, 0x4b800000, v3
	v_cmp_gt_f32_e32 vcc, s25, v3
	v_lshl_add_u64 v[24:25], v[10:11], 0, s[18:19]
	s_nop 0
	v_cndmask_b32_e32 v3, v3, v8, vcc
	v_rsq_f32_e32 v3, v3
	s_nop 0
	v_mul_f32_e32 v4, 0x45800000, v3
	v_cndmask_b32_e32 v4, v3, v4, vcc
	v_pk_mul_f32 v[8:9], v[30:31], v[4:5] op_sel_hi:[1,0]
	v_pk_mul_f32 v[12:13], v[40:41], v[4:5] op_sel_hi:[1,0]
	v_pk_mul_f32 v[6:7], v[6:7], v[4:5] op_sel_hi:[1,0]
	v_pk_mul_f32 v[4:5], v[22:23], v[4:5] op_sel_hi:[1,0]
	v_bfe_u32 v26, v12, 16, 1
	v_bfe_u32 v3, v5, 16, 1
	v_add3_u32 v12, v12, v26, s26
	v_add3_u32 v3, v5, v3, s26
	v_bfe_u32 v5, v8, 16, 1
	v_bfe_u32 v26, v7, 16, 1
	v_bfe_u32 v23, v13, 16, 1
	v_add3_u32 v7, v7, v26, s26
	v_add3_u32 v5, v8, v5, s26
	v_add3_u32 v13, v13, v23, s26
	v_bfe_u32 v23, v6, 16, 1
	v_lshrrev_b32_e32 v8, 16, v5
	v_lshrrev_b32_e32 v5, 16, v7
	v_bfe_u32 v22, v4, 16, 1
	v_add3_u32 v6, v6, v23, s26
	v_and_or_b32 v5, v3, s24, v5
	v_mul_f32_e32 v3, 0x4b800000, v2
	v_cmp_gt_f32_e32 vcc, s25, v2
	v_add3_u32 v4, v4, v22, s26
	v_lshrrev_b32_e32 v6, 16, v6
	v_cndmask_b32_e32 v2, v2, v3, vcc
	v_bfe_u32 v22, v9, 16, 1
	v_and_or_b32 v4, v4, s24, v6
	v_rsq_f32_e32 v6, v2
	v_add3_u32 v9, v9, v22, s26
	v_lshrrev_b32_e32 v9, 16, v9
	v_and_or_b32 v3, v13, s24, v9
	v_and_or_b32 v2, v12, s24, v8
	global_store_dwordx4 v[24:25], v[2:5], off
	v_pk_mul_f32 v[8:9], v[38:39], v[50:51]
	v_pk_mul_f32 v[12:13], v[36:37], v[52:53]
	v_mul_f32_e32 v2, 0x45800000, v6
	v_cndmask_b32_e32 v2, v6, v2, vcc
	v_pk_mul_f32 v[4:5], v[34:35], v[2:3] op_sel_hi:[1,0]
	v_pk_mul_f32 v[6:7], v[56:57], v[2:3] op_sel_hi:[1,0]
	v_pk_mul_f32 v[8:9], v[8:9], v[2:3] op_sel_hi:[1,0]
	v_pk_mul_f32 v[2:3], v[12:13], v[2:3] op_sel_hi:[1,0]
	v_bfe_u32 v22, v7, 16, 1
	v_bfe_u32 v12, v3, 16, 1
	v_bfe_u32 v13, v2, 16, 1
	v_bfe_u32 v23, v6, 16, 1
	v_add3_u32 v6, v6, v23, s26
	v_add3_u32 v7, v7, v22, s26
	v_add3_u32 v2, v2, v13, s26
	v_add3_u32 v3, v3, v12, s26
	v_bfe_u32 v12, v4, 16, 1
	v_bfe_u32 v13, v5, 16, 1
	v_bfe_u32 v22, v8, 16, 1
	v_bfe_u32 v23, v9, 16, 1
	v_add3_u32 v9, v9, v23, s26
	v_add3_u32 v8, v8, v22, s26
	v_add3_u32 v5, v5, v13, s26
	v_add3_u32 v4, v4, v12, s26
	v_lshrrev_b32_e32 v12, 16, v4
	v_lshrrev_b32_e32 v13, 16, v5
	v_lshrrev_b32_e32 v4, 16, v8
	v_lshrrev_b32_e32 v5, 16, v9
	v_and_or_b32 v5, v3, s24, v5
	v_and_or_b32 v4, v2, s24, v4
	v_and_or_b32 v3, v7, s24, v13
	v_and_or_b32 v2, v6, s24, v12
	v_lshl_add_u64 v[6:7], v[10:11], 0, s[16:17]
	s_cselect_b64 s[16:17], -1, 0
	global_store_dwordx4 v[6:7], v[2:5], off
	s_branch .LBB0_497
